# band iterations (last two key blocks) moved into the pipelined body via a reversed padded bias table in LDS
# speedup vs baseline: 1.0198x; 1.0028x over previous
.LBB0_195:
	v_readlane_b32 s68, v240, 16
	v_readlane_b32 s84, v240, 29
	v_readlane_b32 s98, v240, 27
	s_andn2_b64 vcc, exec, s[46:47]
	v_readlane_b32 s69, v240, 17
	v_readlane_b32 s70, v240, 18
	v_readlane_b32 s71, v240, 19
	v_readlane_b32 s72, v240, 20
	v_readlane_b32 s73, v240, 21
	v_readlane_b32 s74, v240, 22
	v_readlane_b32 s75, v240, 23
	v_readlane_b32 s85, v240, 30
	s_mov_b64 s[86:87], s[50:51]
	v_readlane_b32 s99, v240, 28
	v_readlane_b32 s58, v240, 24
	s_cbranch_vccnz .LBB0_226
	s_mov_b32 s20, s81
	v_readlane_b32 s0, v242, 49
	v_readlane_b32 s1, v242, 50
	s_andn2_b64 vcc, exec, s[0:1]
	s_cbranch_vccnz .LBB0_225
	v_readlane_b32 s47, v240, 33
	s_lshl_b32 s0, s47, 4
	v_readlane_b32 s2, v242, 12
	v_readlane_b32 s3, v242, 13
	s_add_u32 s0, s2, s0
	s_addc_u32 s1, s3, 0
	s_lshl_b32 s2, s47, 9
	s_add_u32 s2, s68, s2
	s_addc_u32 s3, s69, 0
	v_readlane_b32 s21, v243, 3
	s_bfe_u32 s4, s21, 0x30003
	s_lshl_b32 s4, s4, 7
	v_sub_u32_e32 v2, 0xff, v172
	v_min_i32_e32 v3, v2, v184
	v_max_i32_e32 v3, 0, v3
	v_add_u32_e32 v3, s4, v3
	v_lshlrev_b32_e32 v3, 2, v3
	global_load_dword v4, v3, s[76:77]
	v_lshlrev_b32_e32 v5, 2, v172
	v_add_u32_e32 v5, 0x20800, v5
	v_cmp_gt_i32_e32 vcc, 0, v2
	s_waitcnt vmcnt(0)
	v_cndmask_b32_e32 v4, v4, v173, vcc
	v_cmp_gt_u32_e32 vcc, 0x180, v172
	s_and_saveexec_b64 s[6:7], vcc
	ds_write_b32 v5, v4
	s_or_b64 exec, exec, s[6:7]
	s_branch .LBB0_199

.LBB0_205:
	s_cmp_lt_i32 s26, 1
	s_cbranch_scc1 .Lfa_old
	s_cmp_lt_i32 s26, s5
	s_cbranch_scc1 .Lfa_body
	s_branch .Lfa_band

.Lfa_band:
	v_add_u32_e32 v0, s20, v156
	v_add_u32_e32 v2, v0, v148
	v_add_u32_e32 v3, v0, v150
	v_add_u32_e32 v4, v0, v152
	v_add_u32_e32 v5, v0, v154
	v_add_u32_e32 v0, s20, v157
	v_add_u32_e32 v0, 0x10000, v0
	v_add_u32_e32 v6, v0, v149
	v_add_u32_e32 v7, v0, v151
	v_add_u32_e32 v8, v0, v153
	v_add_u32_e32 v9, v0, v155
	v_subrev_u32_e32 v10, s86, v144
	v_subrev_u32_e32 v11, s76, v146
	s_and_b32 s16, s6, 0x8000
	s_cbranch_scc0 .Lfa_top_b0
.Lfa_top_b1:
	s_waitcnt vmcnt(0) lgkmcnt(0)
	s_barrier
	ds_read_b128 v[160:163], v2 offset:32768
	ds_read_b128 v[164:167], v2 offset:40960
	ds_read_b128 v[168:171], v3 offset:32768
	ds_read_b128 v[224:227], v3 offset:40960
	ds_read_b128 v[228:231], v4 offset:32768
	ds_read_b128 v[232:235], v4 offset:40960
	ds_read_b128 v[236:239], v5 offset:32768
	ds_read_b128 v[244:247], v5 offset:40960
	ds_read_b128 v[248:251], v2 offset:49152
	ds_read_b128 v[252:255], v2 offset:57344
	s_mov_b32 s80, 0
	v_lshlrev_b32_e32 v12, 2, v158
	v_sub_u32_e32 v12, 0x20a20, v12
	s_waitcnt lgkmcnt(8)
	v_mfma_f32_32x32x16_bf16 v[96:111], v[160:163], v[128:131], v[80:95]
	ds_read_b128 v[160:163], v3 offset:49152
	s_cmp_ge_u32 s26, s23
	s_cbranch_scc1 .Lfa_nd0_b1
	s_sub_i32 s16, s8, 64
	s_mov_b32 s17, 0
	s_lshl_b64 s[16:17], s[16:17], 11
	s_add_u32 s16, s16, s86
	s_addc_u32 s17, s17, s87
	s_add_u32 s18, s76, s6
	s_addc_u32 s19, s77, s7
	s_add_u32 s18, s18, 0x6d08000
	s_addc_u32 s19, s19, 0
	s_add_i32 m0, s24, 0x0
	s_nop 0
	global_load_lds_dwordx4 v10, s[16:17]
.Lfa_nd0_b1:
	v_mfma_f32_32x32x16_bf16 v[112:127], v[164:167], v[128:131], v[80:95]
	ds_read_b128 v[164:167], v3 offset:57344
	s_cmp_ge_u32 s26, s23
	s_cbranch_scc1 .Lfa_nd1_b1
	s_add_i32 m0, s24, 0x2000
	s_add_u32 s16, s16, 0x10000
	s_addc_u32 s17, s17, 0
	global_load_lds_dwordx4 v10, s[16:17]
.Lfa_nd1_b1:
	s_waitcnt lgkmcnt(8)
	v_mfma_f32_32x32x16_bf16 v[96:111], v[168:171], v[132:135], v[96:111]
	ds_read_b128 v[168:171], v4 offset:49152
	s_cmp_ge_u32 s26, s23
	s_cbranch_scc1 .Lfa_nd2_b1
	s_add_i32 m0, s24, 0x10000
	s_nop 0
	global_load_lds_dwordx4 v11, s[18:19]
.Lfa_nd2_b1:
	v_mfma_f32_32x32x16_bf16 v[112:127], v[224:227], v[132:135], v[112:127]
	ds_read_b128 v[224:227], v4 offset:57344
	s_cmp_ge_u32 s26, s23
	s_cbranch_scc1 .Lfa_nd3_b1
	s_add_i32 m0, s24, 0x12000
	s_add_u32 s18, s18, 0x2000
	s_addc_u32 s19, s19, 0
	global_load_lds_dwordx4 v11, s[18:19]
.Lfa_nd3_b1:
	s_waitcnt lgkmcnt(8)
	v_mfma_f32_32x32x16_bf16 v[96:111], v[228:231], v[136:139], v[96:111]
	ds_read_b128 v[228:231], v5 offset:49152
	s_cmp_ge_u32 s26, s23
	s_cbranch_scc1 .Lfa_nd4_b1
	s_add_i32 m0, s24, 0x4000
	s_add_u32 s16, s16, 0x10000
	s_addc_u32 s17, s17, 0
	global_load_lds_dwordx4 v10, s[16:17]
.Lfa_nd4_b1:
	v_mfma_f32_32x32x16_bf16 v[112:127], v[232:235], v[136:139], v[112:127]
	ds_read_b128 v[232:235], v5 offset:57344
	s_cmp_ge_u32 s26, s23
	s_cbranch_scc1 .Lfa_nd5_b1
	s_add_i32 m0, s24, 0x6000
	s_add_u32 s16, s16, 0x10000
	s_addc_u32 s17, s17, 0
	global_load_lds_dwordx4 v10, s[16:17]
.Lfa_nd5_b1:
	s_waitcnt lgkmcnt(8)
	v_mfma_f32_32x32x16_bf16 v[96:111], v[236:239], v[140:143], v[96:111]
	ds_read_b128 v[236:239], v6 offset:32768
	s_cmp_ge_u32 s26, s23
	s_cbranch_scc1 .Lfa_nd6_b1
	s_add_i32 m0, s24, 0x14000
	s_add_u32 s18, s18, 0x2000
	s_addc_u32 s19, s19, 0
	global_load_lds_dwordx4 v11, s[18:19]
.Lfa_nd6_b1:
	v_mfma_f32_32x32x16_bf16 v[112:127], v[244:247], v[140:143], v[112:127]
	ds_read_b128 v[244:247], v6 offset:36864
	s_cmp_ge_u32 s26, s23
	s_cbranch_scc1 .Lfa_nd7_b1
	s_add_i32 m0, s24, 0x16000
	s_add_u32 s18, s18, 0x2000
	s_addc_u32 s19, s19, 0
	global_load_lds_dwordx4 v11, s[18:19]
.Lfa_nd7_b1:
	s_mov_b64 s[18:19], 0
	ds_read_b32 v192, v12 offset:0
	ds_read_b32 v193, v12 offset:4
	ds_read_b32 v194, v12 offset:8
	ds_read_b32 v195, v12 offset:12
	ds_read_b32 v196, v12 offset:16
	ds_read_b32 v197, v12 offset:20
	ds_read_b32 v198, v12 offset:24
	ds_read_b32 v199, v12 offset:28
	ds_read_b32 v200, v12 offset:64
	ds_read_b32 v201, v12 offset:68
	ds_read_b32 v202, v12 offset:72
	ds_read_b32 v203, v12 offset:76
	ds_read_b32 v204, v12 offset:80
	ds_read_b32 v205, v12 offset:84
	ds_read_b32 v206, v12 offset:88
	ds_read_b32 v207, v12 offset:92
	ds_read_b32 v208, v12 offset:128
	ds_read_b32 v209, v12 offset:132
	ds_read_b32 v210, v12 offset:136
	ds_read_b32 v211, v12 offset:140
	ds_read_b32 v212, v12 offset:144
	ds_read_b32 v213, v12 offset:148
	ds_read_b32 v214, v12 offset:152
	ds_read_b32 v215, v12 offset:156
	ds_read_b32 v216, v12 offset:192
	ds_read_b32 v217, v12 offset:196
	ds_read_b32 v218, v12 offset:200
	ds_read_b32 v219, v12 offset:204
	ds_read_b32 v220, v12 offset:208
	ds_read_b32 v221, v12 offset:212
	ds_read_b32 v222, v12 offset:216
	ds_read_b32 v223, v12 offset:220
	s_waitcnt lgkmcnt(0)
	v_add_f32_e32 v96, v96, v192
	v_add_f32_e32 v97, v97, v193
	v_add_f32_e32 v98, v98, v194
	v_add_f32_e32 v99, v99, v195
	v_add_f32_e32 v100, v100, v196
	v_add_f32_e32 v101, v101, v197
	v_add_f32_e32 v102, v102, v198
	v_add_f32_e32 v103, v103, v199
	v_add_f32_e32 v104, v104, v200
	v_add_f32_e32 v105, v105, v201
	v_add_f32_e32 v106, v106, v202
	v_add_f32_e32 v107, v107, v203
	v_add_f32_e32 v108, v108, v204
	v_add_f32_e32 v109, v109, v205
	v_add_f32_e32 v110, v110, v206
	v_add_f32_e32 v111, v111, v207
	v_add_f32_e32 v112, v112, v208
	v_add_f32_e32 v113, v113, v209
	v_add_f32_e32 v114, v114, v210
	v_add_f32_e32 v115, v115, v211
	v_add_f32_e32 v116, v116, v212
	v_add_f32_e32 v117, v117, v213
	v_add_f32_e32 v118, v118, v214
	v_add_f32_e32 v119, v119, v215
	v_add_f32_e32 v120, v120, v216
	v_add_f32_e32 v121, v121, v217
	v_add_f32_e32 v122, v122, v218
	v_add_f32_e32 v123, v123, v219
	v_add_f32_e32 v124, v124, v220
	v_add_f32_e32 v125, v125, v221
	v_add_f32_e32 v126, v126, v222
	v_add_f32_e32 v127, v127, v223
	v_max3_f32 v190, v96, v97, v98
	v_max3_f32 v190, v190, v99, v100
	v_max3_f32 v190, v190, v101, v102
	v_max3_f32 v190, v190, v103, v104
	v_max3_f32 v190, v190, v105, v106
	v_max3_f32 v190, v190, v107, v108
	v_max3_f32 v190, v190, v109, v110
	v_max3_f32 v190, v190, v111, v111
	v_max3_f32 v191, v112, v113, v114
	v_max3_f32 v191, v191, v115, v116
	v_max3_f32 v191, v191, v117, v118
	v_max3_f32 v191, v191, v119, v120
	v_max3_f32 v191, v191, v121, v122
	v_max3_f32 v191, v191, v123, v124
	v_max3_f32 v191, v191, v125, v126
	v_max3_f32 v191, v191, v127, v127
	v_max_f32_e32 v0, v190, v191
	s_nop 0
	v_cmp_lt_f32_e32 vcc, s67, v0
	s_cbranch_vccnz .Lfa_rareA_b1
.Lfa_retA_b1:
	s_waitcnt lgkmcnt(8)
	v_mfma_f32_32x32x16_bf16 v[192:207], v[248:251], v[128:131], v[80:95]
	ds_read_b128 v[248:251], v6 offset:40960
	v_exp_f32_e32 v96, v96
	v_exp_f32_e32 v97, v97
	v_exp_f32_e32 v98, v98
	v_exp_f32_e32 v99, v99
	v_exp_f32_e32 v100, v100
	v_mfma_f32_32x32x16_bf16 v[208:223], v[252:255], v[128:131], v[80:95]
	ds_read_b128 v[252:255], v6 offset:45056
	v_exp_f32_e32 v101, v101
	v_exp_f32_e32 v102, v102
	v_exp_f32_e32 v103, v103
	v_add_f32_e32 v159, v159, v96
	v_add_f32_e32 v159, v159, v97
	s_waitcnt lgkmcnt(8)
	v_mfma_f32_32x32x16_bf16 v[192:207], v[160:163], v[132:135], v[192:207]
	ds_read_b128 v[160:163], v7 offset:32768
	v_add_f32_e32 v159, v159, v98
	v_add_f32_e32 v159, v159, v99
	v_cvt_pk_bf16_f32 v96, v96, v97
	v_cvt_pk_bf16_f32 v97, v98, v99
	v_add_f32_e32 v159, v159, v100
	v_mfma_f32_32x32x16_bf16 v[208:223], v[164:167], v[132:135], v[208:223]
	ds_read_b128 v[164:167], v7 offset:36864
	v_add_f32_e32 v159, v159, v101
	v_cvt_pk_bf16_f32 v98, v100, v101
	v_cvt_pk_bf16_f32 v99, v102, v103
	v_add_f32_e32 v159, v159, v102
	v_add_f32_e32 v159, v159, v103
	s_waitcnt lgkmcnt(8)
	v_mfma_f32_32x32x16_bf16 v[192:207], v[168:171], v[136:139], v[192:207]
	ds_read_b128 v[168:171], v7 offset:40960
	v_exp_f32_e32 v104, v104
	v_exp_f32_e32 v105, v105
	v_exp_f32_e32 v106, v106
	v_exp_f32_e32 v107, v107
	v_exp_f32_e32 v108, v108
	v_mfma_f32_32x32x16_bf16 v[208:223], v[224:227], v[136:139], v[208:223]
	ds_read_b128 v[224:227], v7 offset:45056
	v_exp_f32_e32 v109, v109
	v_exp_f32_e32 v110, v110
	v_exp_f32_e32 v111, v111
	v_add_f32_e32 v159, v159, v104
	v_add_f32_e32 v159, v159, v105
	s_waitcnt lgkmcnt(8)
	v_mfma_f32_32x32x16_bf16 v[192:207], v[228:231], v[140:143], v[192:207]
	ds_read_b128 v[228:231], v8 offset:32768
	v_add_f32_e32 v159, v159, v106
	v_add_f32_e32 v159, v159, v107
	v_cvt_pk_bf16_f32 v104, v104, v105
	v_cvt_pk_bf16_f32 v105, v106, v107
	v_add_f32_e32 v159, v159, v108
	v_mfma_f32_32x32x16_bf16 v[208:223], v[232:235], v[140:143], v[208:223]
	ds_read_b128 v[232:235], v8 offset:36864
	v_add_f32_e32 v159, v159, v109
	v_cvt_pk_bf16_f32 v106, v108, v109
	v_cvt_pk_bf16_f32 v107, v110, v111
	v_add_f32_e32 v159, v159, v110
	v_add_f32_e32 v159, v159, v111
	s_waitcnt lgkmcnt(8)
	v_mfma_f32_32x32x16_bf16 v[64:79], v[236:239], v[96:99], v[64:79]
	ds_read_b128 v[236:239], v8 offset:40960
	v_exp_f32_e32 v112, v112
	v_exp_f32_e32 v113, v113
	v_exp_f32_e32 v114, v114
	v_exp_f32_e32 v115, v115
	v_exp_f32_e32 v116, v116
	v_mfma_f32_32x32x16_bf16 v[48:63], v[244:247], v[96:99], v[48:63]
	ds_read_b128 v[244:247], v8 offset:45056
	v_exp_f32_e32 v117, v117
	v_exp_f32_e32 v118, v118
	v_exp_f32_e32 v119, v119
	v_add_f32_e32 v159, v159, v112
	v_add_f32_e32 v159, v159, v113
	s_waitcnt lgkmcnt(8)
	v_mfma_f32_32x32x16_bf16 v[32:47], v[248:251], v[96:99], v[32:47]
	ds_read_b128 v[248:251], v9 offset:32768
	v_add_f32_e32 v159, v159, v114
	v_add_f32_e32 v159, v159, v115
	v_cvt_pk_bf16_f32 v112, v112, v113
	v_cvt_pk_bf16_f32 v113, v114, v115
	v_add_f32_e32 v159, v159, v116
	v_mfma_f32_32x32x16_bf16 v[16:31], v[252:255], v[96:99], v[16:31]
	ds_read_b128 v[252:255], v9 offset:36864
	v_add_f32_e32 v159, v159, v117
	v_cvt_pk_bf16_f32 v114, v116, v117
	v_cvt_pk_bf16_f32 v115, v118, v119
	v_add_f32_e32 v159, v159, v118
	v_add_f32_e32 v159, v159, v119
	s_waitcnt lgkmcnt(8)
	v_mfma_f32_32x32x16_bf16 v[64:79], v[160:163], v[104:107], v[64:79]
	ds_read_b128 v[160:163], v9 offset:40960
	v_exp_f32_e32 v120, v120
	v_exp_f32_e32 v121, v121
	v_exp_f32_e32 v122, v122
	v_exp_f32_e32 v123, v123
	v_exp_f32_e32 v124, v124
	v_mfma_f32_32x32x16_bf16 v[48:63], v[164:167], v[104:107], v[48:63]
	ds_read_b128 v[164:167], v9 offset:45056
	v_exp_f32_e32 v125, v125
	v_exp_f32_e32 v126, v126
	v_exp_f32_e32 v127, v127
	v_add_f32_e32 v159, v159, v120
	v_add_f32_e32 v159, v159, v121
	s_waitcnt lgkmcnt(8)
	v_mfma_f32_32x32x16_bf16 v[32:47], v[168:171], v[104:107], v[32:47]
	ds_read_b128 v[168:171], v6 offset:49152
	v_add_f32_e32 v159, v159, v122
	v_add_f32_e32 v159, v159, v123
	v_cvt_pk_bf16_f32 v120, v120, v121
	v_cvt_pk_bf16_f32 v121, v122, v123
	v_add_f32_e32 v159, v159, v124
	v_mfma_f32_32x32x16_bf16 v[16:31], v[224:227], v[104:107], v[16:31]
	ds_read_b128 v[224:227], v6 offset:53248
	v_add_f32_e32 v159, v159, v125
	v_cvt_pk_bf16_f32 v122, v124, v125
	v_cvt_pk_bf16_f32 v123, v126, v127
	v_add_f32_e32 v159, v159, v126
	v_add_f32_e32 v159, v159, v127
	ds_read_b32 v100, v12 offset:256
	ds_read_b32 v101, v12 offset:260
	ds_read_b32 v102, v12 offset:264
	ds_read_b32 v103, v12 offset:268
	ds_read_b32 v108, v12 offset:272
	ds_read_b32 v109, v12 offset:276
	ds_read_b32 v110, v12 offset:280
	ds_read_b32 v111, v12 offset:284
	ds_read_b32 v116, v12 offset:320
	ds_read_b32 v117, v12 offset:324
	ds_read_b32 v118, v12 offset:328
	ds_read_b32 v119, v12 offset:332
	ds_read_b32 v124, v12 offset:336
	ds_read_b32 v125, v12 offset:340
	ds_read_b32 v126, v12 offset:344
	ds_read_b32 v127, v12 offset:348
	s_waitcnt lgkmcnt(0)
	v_add_f32_e32 v192, v192, v100
	v_add_f32_e32 v193, v193, v101
	v_add_f32_e32 v194, v194, v102
	v_add_f32_e32 v195, v195, v103
	v_add_f32_e32 v196, v196, v108
	v_add_f32_e32 v197, v197, v109
	v_add_f32_e32 v198, v198, v110
	v_add_f32_e32 v199, v199, v111
	v_add_f32_e32 v200, v200, v116
	v_add_f32_e32 v201, v201, v117
	v_add_f32_e32 v202, v202, v118
	v_add_f32_e32 v203, v203, v119
	v_add_f32_e32 v204, v204, v124
	v_add_f32_e32 v205, v205, v125
	v_add_f32_e32 v206, v206, v126
	v_add_f32_e32 v207, v207, v127
	ds_read_b32 v100, v12 offset:384
	ds_read_b32 v101, v12 offset:388
	ds_read_b32 v102, v12 offset:392
	ds_read_b32 v103, v12 offset:396
	ds_read_b32 v108, v12 offset:400
	ds_read_b32 v109, v12 offset:404
	ds_read_b32 v110, v12 offset:408
	ds_read_b32 v111, v12 offset:412
	ds_read_b32 v116, v12 offset:448
	ds_read_b32 v117, v12 offset:452
	ds_read_b32 v118, v12 offset:456
	ds_read_b32 v119, v12 offset:460
	ds_read_b32 v124, v12 offset:464
	ds_read_b32 v125, v12 offset:468
	ds_read_b32 v126, v12 offset:472
	ds_read_b32 v127, v12 offset:476
	s_waitcnt lgkmcnt(0)
	v_add_f32_e32 v208, v208, v100
	v_add_f32_e32 v209, v209, v101
	v_add_f32_e32 v210, v210, v102
	v_add_f32_e32 v211, v211, v103
	v_add_f32_e32 v212, v212, v108
	v_add_f32_e32 v213, v213, v109
	v_add_f32_e32 v214, v214, v110
	v_add_f32_e32 v215, v215, v111
	v_add_f32_e32 v216, v216, v116
	v_add_f32_e32 v217, v217, v117
	v_add_f32_e32 v218, v218, v118
	v_add_f32_e32 v219, v219, v119
	v_add_f32_e32 v220, v220, v124
	v_add_f32_e32 v221, v221, v125
	v_add_f32_e32 v222, v222, v126
	v_add_f32_e32 v223, v223, v127
	v_max3_f32 v190, v192, v193, v194
	v_max3_f32 v190, v190, v195, v196
	v_max3_f32 v190, v190, v197, v198
	v_max3_f32 v190, v190, v199, v200
	v_max3_f32 v190, v190, v201, v202
	v_max3_f32 v190, v190, v203, v204
	v_max3_f32 v190, v190, v205, v206
	v_max3_f32 v190, v190, v207, v207
	v_max3_f32 v191, v208, v209, v210
	v_max3_f32 v191, v191, v211, v212
	v_max3_f32 v191, v191, v213, v214
	v_max3_f32 v191, v191, v215, v216
	v_max3_f32 v191, v191, v217, v218
	v_max3_f32 v191, v191, v219, v220
	v_max3_f32 v191, v191, v221, v222
	v_max3_f32 v191, v191, v223, v223
	v_max_f32_e32 v0, v190, v191
	s_nop 0
	v_cmp_lt_f32_e32 vcc, s67, v0
	s_or_b64 vcc, vcc, s[18:19]
	s_cbranch_vccnz .Lfa_rareB_b1
.Lfa_retB_b1:
	s_waitcnt lgkmcnt(8)
	v_mfma_f32_32x32x16_bf16 v[64:79], v[228:231], v[112:115], v[64:79]
	ds_read_b128 v[228:231], v6 offset:57344
	v_exp_f32_e32 v192, v192
	v_exp_f32_e32 v193, v193
	v_exp_f32_e32 v194, v194
	v_exp_f32_e32 v195, v195
	v_exp_f32_e32 v196, v196
	v_mfma_f32_32x32x16_bf16 v[48:63], v[232:235], v[112:115], v[48:63]
	ds_read_b128 v[232:235], v6 offset:61440
	v_exp_f32_e32 v197, v197
	v_exp_f32_e32 v198, v198
	v_exp_f32_e32 v199, v199
	v_add_f32_e32 v159, v159, v192
	v_add_f32_e32 v159, v159, v193
	s_waitcnt lgkmcnt(8)
	v_mfma_f32_32x32x16_bf16 v[32:47], v[236:239], v[112:115], v[32:47]
	ds_read_b128 v[236:239], v7 offset:49152
	v_add_f32_e32 v159, v159, v194
	v_add_f32_e32 v159, v159, v195
	v_cvt_pk_bf16_f32 v192, v192, v193
	v_cvt_pk_bf16_f32 v193, v194, v195
	v_add_f32_e32 v159, v159, v196
	v_mfma_f32_32x32x16_bf16 v[16:31], v[244:247], v[112:115], v[16:31]
	ds_read_b128 v[244:247], v7 offset:53248
	v_add_f32_e32 v159, v159, v197
	v_cvt_pk_bf16_f32 v194, v196, v197
	v_cvt_pk_bf16_f32 v195, v198, v199
	v_add_f32_e32 v159, v159, v198
	v_add_f32_e32 v159, v159, v199
	s_waitcnt lgkmcnt(8)
	v_mfma_f32_32x32x16_bf16 v[64:79], v[248:251], v[120:123], v[64:79]
	ds_read_b128 v[248:251], v7 offset:57344
	v_mfma_f32_32x32x16_bf16 v[48:63], v[252:255], v[120:123], v[48:63]
	ds_read_b128 v[252:255], v7 offset:61440
	s_waitcnt lgkmcnt(8)
	v_mfma_f32_32x32x16_bf16 v[32:47], v[160:163], v[120:123], v[32:47]
	ds_read_b128 v[160:163], v8 offset:49152
	v_mfma_f32_32x32x16_bf16 v[16:31], v[164:167], v[120:123], v[16:31]
	ds_read_b128 v[164:167], v8 offset:53248
	s_cmp_lg_u32 s80, 0
	s_cbranch_scc1 .Lfa_fixO_b1
.Lfa_retO_b1:
	s_waitcnt lgkmcnt(8)
	v_mfma_f32_32x32x16_bf16 v[64:79], v[168:171], v[192:195], v[64:79]
	ds_read_b128 v[168:171], v8 offset:57344
	v_exp_f32_e32 v200, v200
	v_exp_f32_e32 v201, v201
	v_exp_f32_e32 v202, v202
	v_exp_f32_e32 v203, v203
	v_exp_f32_e32 v204, v204
	v_mfma_f32_32x32x16_bf16 v[48:63], v[224:227], v[192:195], v[48:63]
	ds_read_b128 v[224:227], v8 offset:61440
	v_exp_f32_e32 v205, v205
	v_exp_f32_e32 v206, v206
	v_exp_f32_e32 v207, v207
	v_add_f32_e32 v159, v159, v200
	v_add_f32_e32 v159, v159, v201
	s_waitcnt lgkmcnt(8)
	v_mfma_f32_32x32x16_bf16 v[32:47], v[228:231], v[192:195], v[32:47]
	ds_read_b128 v[228:231], v9 offset:49152
	v_add_f32_e32 v159, v159, v202
	v_add_f32_e32 v159, v159, v203
	v_cvt_pk_bf16_f32 v200, v200, v201
	v_cvt_pk_bf16_f32 v201, v202, v203
	v_add_f32_e32 v159, v159, v204
	v_mfma_f32_32x32x16_bf16 v[16:31], v[232:235], v[192:195], v[16:31]
	ds_read_b128 v[232:235], v9 offset:53248
	v_add_f32_e32 v159, v159, v205
	v_cvt_pk_bf16_f32 v202, v204, v205
	v_cvt_pk_bf16_f32 v203, v206, v207
	v_add_f32_e32 v159, v159, v206
	v_add_f32_e32 v159, v159, v207
	s_waitcnt lgkmcnt(8)
	v_mfma_f32_32x32x16_bf16 v[64:79], v[236:239], v[200:203], v[64:79]
	ds_read_b128 v[236:239], v9 offset:57344
	v_exp_f32_e32 v208, v208
	v_exp_f32_e32 v209, v209
	v_exp_f32_e32 v210, v210
	v_exp_f32_e32 v211, v211
	v_exp_f32_e32 v212, v212
	v_mfma_f32_32x32x16_bf16 v[48:63], v[244:247], v[200:203], v[48:63]
	ds_read_b128 v[244:247], v9 offset:61440
	v_exp_f32_e32 v213, v213
	v_exp_f32_e32 v214, v214
	v_exp_f32_e32 v215, v215
	v_add_f32_e32 v159, v159, v208
	v_add_f32_e32 v159, v159, v209
	s_waitcnt lgkmcnt(8)
	v_mfma_f32_32x32x16_bf16 v[32:47], v[248:251], v[200:203], v[32:47]
	v_add_f32_e32 v159, v159, v210
	v_add_f32_e32 v159, v159, v211
	v_cvt_pk_bf16_f32 v208, v208, v209
	v_cvt_pk_bf16_f32 v209, v210, v211
	v_add_f32_e32 v159, v159, v212
	v_mfma_f32_32x32x16_bf16 v[16:31], v[252:255], v[200:203], v[16:31]
	v_add_f32_e32 v159, v159, v213
	v_cvt_pk_bf16_f32 v210, v212, v213
	v_cvt_pk_bf16_f32 v211, v214, v215
	v_add_f32_e32 v159, v159, v214
	v_add_f32_e32 v159, v159, v215
	s_waitcnt lgkmcnt(6)
	v_mfma_f32_32x32x16_bf16 v[64:79], v[160:163], v[208:211], v[64:79]
	v_exp_f32_e32 v216, v216
	v_exp_f32_e32 v217, v217
	v_exp_f32_e32 v218, v218
	v_exp_f32_e32 v219, v219
	v_exp_f32_e32 v220, v220
	v_mfma_f32_32x32x16_bf16 v[48:63], v[164:167], v[208:211], v[48:63]
	v_exp_f32_e32 v221, v221
	v_exp_f32_e32 v222, v222
	v_exp_f32_e32 v223, v223
	v_add_f32_e32 v159, v159, v216
	v_add_f32_e32 v159, v159, v217
	s_waitcnt lgkmcnt(4)
	v_mfma_f32_32x32x16_bf16 v[32:47], v[168:171], v[208:211], v[32:47]
	v_add_f32_e32 v159, v159, v218
	v_add_f32_e32 v159, v159, v219
	v_cvt_pk_bf16_f32 v216, v216, v217
	v_cvt_pk_bf16_f32 v217, v218, v219
	v_add_f32_e32 v159, v159, v220
	v_mfma_f32_32x32x16_bf16 v[16:31], v[224:227], v[208:211], v[16:31]
	v_add_f32_e32 v159, v159, v221
	v_cvt_pk_bf16_f32 v218, v220, v221
	v_cvt_pk_bf16_f32 v219, v222, v223
	v_add_f32_e32 v159, v159, v222
	v_add_f32_e32 v159, v159, v223
	s_waitcnt lgkmcnt(2)
	v_mfma_f32_32x32x16_bf16 v[64:79], v[228:231], v[216:219], v[64:79]
	s_add_i32 s26, s26, 1
	s_add_u32 s6, s6, 0x8000
	v_mfma_f32_32x32x16_bf16 v[48:63], v[232:235], v[216:219], v[48:63]
	s_addc_u32 s7, s7, 0
	s_addk_i32 s8, 0x80
	s_waitcnt lgkmcnt(0)
	v_mfma_f32_32x32x16_bf16 v[32:47], v[236:239], v[216:219], v[32:47]
	v_add_u32_e32 v158, 0xffffff80, v158
	v_mfma_f32_32x32x16_bf16 v[16:31], v[244:247], v[216:219], v[16:31]
	s_cmp_eq_u32 s25, s26
	s_cbranch_scc1 .Lfa_bexit
.Lfa_top_b0:
	s_waitcnt vmcnt(0) lgkmcnt(0)
	s_barrier
	ds_read_b128 v[160:163], v2
	ds_read_b128 v[164:167], v2 offset:8192
	ds_read_b128 v[168:171], v3
	ds_read_b128 v[224:227], v3 offset:8192
	ds_read_b128 v[228:231], v4
	ds_read_b128 v[232:235], v4 offset:8192
	ds_read_b128 v[236:239], v5
	ds_read_b128 v[244:247], v5 offset:8192
	ds_read_b128 v[248:251], v2 offset:16384
	ds_read_b128 v[252:255], v2 offset:24576
	s_mov_b32 s80, 0
	v_lshlrev_b32_e32 v12, 2, v158
	v_sub_u32_e32 v12, 0x20a20, v12
	s_waitcnt lgkmcnt(8)
	v_mfma_f32_32x32x16_bf16 v[96:111], v[160:163], v[128:131], v[80:95]
	ds_read_b128 v[160:163], v3 offset:16384
	s_cmp_ge_u32 s26, s23
	s_cbranch_scc1 .Lfa_nd0_b0
	s_sub_i32 s16, s8, 64
	s_mov_b32 s17, 0
	s_lshl_b64 s[16:17], s[16:17], 11
	s_add_u32 s16, s16, s86
	s_addc_u32 s17, s17, s87
	s_add_u32 s18, s76, s6
	s_addc_u32 s19, s77, s7
	s_add_u32 s18, s18, 0x6d08000
	s_addc_u32 s19, s19, 0
	s_add_i32 m0, s24, 0x8000
	s_nop 0
	global_load_lds_dwordx4 v10, s[16:17]
.Lfa_nd0_b0:
	v_mfma_f32_32x32x16_bf16 v[112:127], v[164:167], v[128:131], v[80:95]
	ds_read_b128 v[164:167], v3 offset:24576
	s_cmp_ge_u32 s26, s23
	s_cbranch_scc1 .Lfa_nd1_b0
	s_add_i32 m0, s24, 0xa000
	s_add_u32 s16, s16, 0x10000
	s_addc_u32 s17, s17, 0
	global_load_lds_dwordx4 v10, s[16:17]
.Lfa_nd1_b0:
	s_waitcnt lgkmcnt(8)
	v_mfma_f32_32x32x16_bf16 v[96:111], v[168:171], v[132:135], v[96:111]
	ds_read_b128 v[168:171], v4 offset:16384
	s_cmp_ge_u32 s26, s23
	s_cbranch_scc1 .Lfa_nd2_b0
	s_add_i32 m0, s24, 0x18000
	s_nop 0
	global_load_lds_dwordx4 v11, s[18:19]
.Lfa_nd2_b0:
	v_mfma_f32_32x32x16_bf16 v[112:127], v[224:227], v[132:135], v[112:127]
	ds_read_b128 v[224:227], v4 offset:24576
	s_cmp_ge_u32 s26, s23
	s_cbranch_scc1 .Lfa_nd3_b0
	s_add_i32 m0, s24, 0x1a000
	s_add_u32 s18, s18, 0x2000
	s_addc_u32 s19, s19, 0
	global_load_lds_dwordx4 v11, s[18:19]
.Lfa_nd3_b0:
	s_waitcnt lgkmcnt(8)
	v_mfma_f32_32x32x16_bf16 v[96:111], v[228:231], v[136:139], v[96:111]
	ds_read_b128 v[228:231], v5 offset:16384
	s_cmp_ge_u32 s26, s23
	s_cbranch_scc1 .Lfa_nd4_b0
	s_add_i32 m0, s24, 0xc000
	s_add_u32 s16, s16, 0x10000
	s_addc_u32 s17, s17, 0
	global_load_lds_dwordx4 v10, s[16:17]
.Lfa_nd4_b0:
	v_mfma_f32_32x32x16_bf16 v[112:127], v[232:235], v[136:139], v[112:127]
	ds_read_b128 v[232:235], v5 offset:24576
	s_cmp_ge_u32 s26, s23
	s_cbranch_scc1 .Lfa_nd5_b0
	s_add_i32 m0, s24, 0xe000
	s_add_u32 s16, s16, 0x10000
	s_addc_u32 s17, s17, 0
	global_load_lds_dwordx4 v10, s[16:17]
.Lfa_nd5_b0:
	s_waitcnt lgkmcnt(8)
	v_mfma_f32_32x32x16_bf16 v[96:111], v[236:239], v[140:143], v[96:111]
	ds_read_b128 v[236:239], v6
	s_cmp_ge_u32 s26, s23
	s_cbranch_scc1 .Lfa_nd6_b0
	s_add_i32 m0, s24, 0x1c000
	s_add_u32 s18, s18, 0x2000
	s_addc_u32 s19, s19, 0
	global_load_lds_dwordx4 v11, s[18:19]
.Lfa_nd6_b0:
	v_mfma_f32_32x32x16_bf16 v[112:127], v[244:247], v[140:143], v[112:127]
	ds_read_b128 v[244:247], v6 offset:4096
	s_cmp_ge_u32 s26, s23
	s_cbranch_scc1 .Lfa_nd7_b0
	s_add_i32 m0, s24, 0x1e000
	s_add_u32 s18, s18, 0x2000
	s_addc_u32 s19, s19, 0
	global_load_lds_dwordx4 v11, s[18:19]

.Lfa_retA_b0:
	s_waitcnt lgkmcnt(8)
	v_mfma_f32_32x32x16_bf16 v[192:207], v[248:251], v[128:131], v[80:95]
	ds_read_b128 v[248:251], v6 offset:8192
	v_exp_f32_e32 v96, v96
	v_exp_f32_e32 v97, v97
	v_exp_f32_e32 v98, v98
	v_exp_f32_e32 v99, v99
	v_exp_f32_e32 v100, v100
	v_mfma_f32_32x32x16_bf16 v[208:223], v[252:255], v[128:131], v[80:95]
	ds_read_b128 v[252:255], v6 offset:12288
	v_exp_f32_e32 v101, v101
	v_exp_f32_e32 v102, v102
	v_exp_f32_e32 v103, v103
	v_add_f32_e32 v159, v159, v96
	v_add_f32_e32 v159, v159, v97
	s_waitcnt lgkmcnt(8)
	v_mfma_f32_32x32x16_bf16 v[192:207], v[160:163], v[132:135], v[192:207]
	ds_read_b128 v[160:163], v7
	v_add_f32_e32 v159, v159, v98
	v_add_f32_e32 v159, v159, v99
	v_cvt_pk_bf16_f32 v96, v96, v97
	v_cvt_pk_bf16_f32 v97, v98, v99
	v_add_f32_e32 v159, v159, v100
	v_mfma_f32_32x32x16_bf16 v[208:223], v[164:167], v[132:135], v[208:223]
	ds_read_b128 v[164:167], v7 offset:4096
	v_add_f32_e32 v159, v159, v101
	v_cvt_pk_bf16_f32 v98, v100, v101
	v_cvt_pk_bf16_f32 v99, v102, v103
	v_add_f32_e32 v159, v159, v102
	v_add_f32_e32 v159, v159, v103
	s_waitcnt lgkmcnt(8)
	v_mfma_f32_32x32x16_bf16 v[192:207], v[168:171], v[136:139], v[192:207]
	ds_read_b128 v[168:171], v7 offset:8192
	v_exp_f32_e32 v104, v104
	v_exp_f32_e32 v105, v105
	v_exp_f32_e32 v106, v106
	v_exp_f32_e32 v107, v107
	v_exp_f32_e32 v108, v108
	v_mfma_f32_32x32x16_bf16 v[208:223], v[224:227], v[136:139], v[208:223]
	ds_read_b128 v[224:227], v7 offset:12288
	v_exp_f32_e32 v109, v109
	v_exp_f32_e32 v110, v110
	v_exp_f32_e32 v111, v111
	v_add_f32_e32 v159, v159, v104
	v_add_f32_e32 v159, v159, v105
	s_waitcnt lgkmcnt(8)
	v_mfma_f32_32x32x16_bf16 v[192:207], v[228:231], v[140:143], v[192:207]
	ds_read_b128 v[228:231], v8
	v_add_f32_e32 v159, v159, v106
	v_add_f32_e32 v159, v159, v107
	v_cvt_pk_bf16_f32 v104, v104, v105
	v_cvt_pk_bf16_f32 v105, v106, v107
	v_add_f32_e32 v159, v159, v108
	v_mfma_f32_32x32x16_bf16 v[208:223], v[232:235], v[140:143], v[208:223]
	ds_read_b128 v[232:235], v8 offset:4096
	v_add_f32_e32 v159, v159, v109
	v_cvt_pk_bf16_f32 v106, v108, v109
	v_cvt_pk_bf16_f32 v107, v110, v111
	v_add_f32_e32 v159, v159, v110
	v_add_f32_e32 v159, v159, v111
	s_waitcnt lgkmcnt(8)
	v_mfma_f32_32x32x16_bf16 v[64:79], v[236:239], v[96:99], v[64:79]
	ds_read_b128 v[236:239], v8 offset:8192
	v_exp_f32_e32 v112, v112
	v_exp_f32_e32 v113, v113
	v_exp_f32_e32 v114, v114
	v_exp_f32_e32 v115, v115
	v_exp_f32_e32 v116, v116
	v_mfma_f32_32x32x16_bf16 v[48:63], v[244:247], v[96:99], v[48:63]
	ds_read_b128 v[244:247], v8 offset:12288
	v_exp_f32_e32 v117, v117
	v_exp_f32_e32 v118, v118
	v_exp_f32_e32 v119, v119
	v_add_f32_e32 v159, v159, v112
	v_add_f32_e32 v159, v159, v113
	s_waitcnt lgkmcnt(8)
	v_mfma_f32_32x32x16_bf16 v[32:47], v[248:251], v[96:99], v[32:47]
	ds_read_b128 v[248:251], v9
	v_add_f32_e32 v159, v159, v114
	v_add_f32_e32 v159, v159, v115
	v_cvt_pk_bf16_f32 v112, v112, v113
	v_cvt_pk_bf16_f32 v113, v114, v115
	v_add_f32_e32 v159, v159, v116
	v_mfma_f32_32x32x16_bf16 v[16:31], v[252:255], v[96:99], v[16:31]
	ds_read_b128 v[252:255], v9 offset:4096
	v_add_f32_e32 v159, v159, v117
	v_cvt_pk_bf16_f32 v114, v116, v117
	v_cvt_pk_bf16_f32 v115, v118, v119
	v_add_f32_e32 v159, v159, v118
	v_add_f32_e32 v159, v159, v119
	s_waitcnt lgkmcnt(8)
	v_mfma_f32_32x32x16_bf16 v[64:79], v[160:163], v[104:107], v[64:79]
	ds_read_b128 v[160:163], v9 offset:8192
	v_exp_f32_e32 v120, v120
	v_exp_f32_e32 v121, v121
	v_exp_f32_e32 v122, v122
	v_exp_f32_e32 v123, v123
	v_exp_f32_e32 v124, v124
	v_mfma_f32_32x32x16_bf16 v[48:63], v[164:167], v[104:107], v[48:63]
	ds_read_b128 v[164:167], v9 offset:12288
	v_exp_f32_e32 v125, v125
	v_exp_f32_e32 v126, v126
	v_exp_f32_e32 v127, v127
	v_add_f32_e32 v159, v159, v120
	v_add_f32_e32 v159, v159, v121
	s_waitcnt lgkmcnt(8)
	v_mfma_f32_32x32x16_bf16 v[32:47], v[168:171], v[104:107], v[32:47]
	ds_read_b128 v[168:171], v6 offset:16384
	v_add_f32_e32 v159, v159, v122
	v_add_f32_e32 v159, v159, v123
	v_cvt_pk_bf16_f32 v120, v120, v121
	v_cvt_pk_bf16_f32 v121, v122, v123
	v_add_f32_e32 v159, v159, v124
	v_mfma_f32_32x32x16_bf16 v[16:31], v[224:227], v[104:107], v[16:31]
	ds_read_b128 v[224:227], v6 offset:20480
	v_add_f32_e32 v159, v159, v125
	v_cvt_pk_bf16_f32 v122, v124, v125
	v_cvt_pk_bf16_f32 v123, v126, v127
	v_add_f32_e32 v159, v159, v126
	v_add_f32_e32 v159, v159, v127
	ds_read_b32 v100, v12 offset:256
	ds_read_b32 v101, v12 offset:260
	ds_read_b32 v102, v12 offset:264
	ds_read_b32 v103, v12 offset:268
	ds_read_b32 v108, v12 offset:272
	ds_read_b32 v109, v12 offset:276
	ds_read_b32 v110, v12 offset:280
	ds_read_b32 v111, v12 offset:284
	ds_read_b32 v116, v12 offset:320
	ds_read_b32 v117, v12 offset:324
	ds_read_b32 v118, v12 offset:328
	ds_read_b32 v119, v12 offset:332
	ds_read_b32 v124, v12 offset:336
	ds_read_b32 v125, v12 offset:340
	ds_read_b32 v126, v12 offset:344
	ds_read_b32 v127, v12 offset:348
	s_waitcnt lgkmcnt(0)
	v_add_f32_e32 v192, v192, v100
	v_add_f32_e32 v193, v193, v101
	v_add_f32_e32 v194, v194, v102
	v_add_f32_e32 v195, v195, v103
	v_add_f32_e32 v196, v196, v108
	v_add_f32_e32 v197, v197, v109
	v_add_f32_e32 v198, v198, v110
	v_add_f32_e32 v199, v199, v111
	v_add_f32_e32 v200, v200, v116
	v_add_f32_e32 v201, v201, v117
	v_add_f32_e32 v202, v202, v118
	v_add_f32_e32 v203, v203, v119
	v_add_f32_e32 v204, v204, v124
	v_add_f32_e32 v205, v205, v125
	v_add_f32_e32 v206, v206, v126
	v_add_f32_e32 v207, v207, v127
	ds_read_b32 v100, v12 offset:384
	ds_read_b32 v101, v12 offset:388
	ds_read_b32 v102, v12 offset:392
	ds_read_b32 v103, v12 offset:396
	ds_read_b32 v108, v12 offset:400
	ds_read_b32 v109, v12 offset:404
	ds_read_b32 v110, v12 offset:408
	ds_read_b32 v111, v12 offset:412
	ds_read_b32 v116, v12 offset:448
	ds_read_b32 v117, v12 offset:452
	ds_read_b32 v118, v12 offset:456
	ds_read_b32 v119, v12 offset:460
	ds_read_b32 v124, v12 offset:464
	ds_read_b32 v125, v12 offset:468
	ds_read_b32 v126, v12 offset:472
	ds_read_b32 v127, v12 offset:476
	s_waitcnt lgkmcnt(0)
	v_add_f32_e32 v208, v208, v100
	v_add_f32_e32 v209, v209, v101
	v_add_f32_e32 v210, v210, v102
	v_add_f32_e32 v211, v211, v103
	v_add_f32_e32 v212, v212, v108
	v_add_f32_e32 v213, v213, v109
	v_add_f32_e32 v214, v214, v110
	v_add_f32_e32 v215, v215, v111
	v_add_f32_e32 v216, v216, v116
	v_add_f32_e32 v217, v217, v117
	v_add_f32_e32 v218, v218, v118
	v_add_f32_e32 v219, v219, v119
	v_add_f32_e32 v220, v220, v124
	v_add_f32_e32 v221, v221, v125
	v_add_f32_e32 v222, v222, v126
	v_add_f32_e32 v223, v223, v127
	v_max3_f32 v190, v192, v193, v194
	v_max3_f32 v190, v190, v195, v196
	v_max3_f32 v190, v190, v197, v198
	v_max3_f32 v190, v190, v199, v200
	v_max3_f32 v190, v190, v201, v202
	v_max3_f32 v190, v190, v203, v204
	v_max3_f32 v190, v190, v205, v206
	v_max3_f32 v190, v190, v207, v207
	v_max3_f32 v191, v208, v209, v210
	v_max3_f32 v191, v191, v211, v212
	v_max3_f32 v191, v191, v213, v214
	v_max3_f32 v191, v191, v215, v216
	v_max3_f32 v191, v191, v217, v218
	v_max3_f32 v191, v191, v219, v220
	v_max3_f32 v191, v191, v221, v222
	v_max3_f32 v191, v191, v223, v223
	v_max_f32_e32 v0, v190, v191
	s_nop 0
	v_cmp_lt_f32_e32 vcc, s67, v0
	s_or_b64 vcc, vcc, s[18:19]
	s_cbranch_vccnz .Lfa_rareB_b0
.Lfa_retB_b0:
	s_waitcnt lgkmcnt(8)
	v_mfma_f32_32x32x16_bf16 v[64:79], v[228:231], v[112:115], v[64:79]
	ds_read_b128 v[228:231], v6 offset:24576
	v_exp_f32_e32 v192, v192
	v_exp_f32_e32 v193, v193
	v_exp_f32_e32 v194, v194
	v_exp_f32_e32 v195, v195
	v_exp_f32_e32 v196, v196
	v_mfma_f32_32x32x16_bf16 v[48:63], v[232:235], v[112:115], v[48:63]
	ds_read_b128 v[232:235], v6 offset:28672
	v_exp_f32_e32 v197, v197
	v_exp_f32_e32 v198, v198
	v_exp_f32_e32 v199, v199
	v_add_f32_e32 v159, v159, v192
	v_add_f32_e32 v159, v159, v193
	s_waitcnt lgkmcnt(8)
	v_mfma_f32_32x32x16_bf16 v[32:47], v[236:239], v[112:115], v[32:47]
	ds_read_b128 v[236:239], v7 offset:16384
	v_add_f32_e32 v159, v159, v194
	v_add_f32_e32 v159, v159, v195
	v_cvt_pk_bf16_f32 v192, v192, v193
	v_cvt_pk_bf16_f32 v193, v194, v195
	v_add_f32_e32 v159, v159, v196
	v_mfma_f32_32x32x16_bf16 v[16:31], v[244:247], v[112:115], v[16:31]
	ds_read_b128 v[244:247], v7 offset:20480
	v_add_f32_e32 v159, v159, v197
	v_cvt_pk_bf16_f32 v194, v196, v197
	v_cvt_pk_bf16_f32 v195, v198, v199
	v_add_f32_e32 v159, v159, v198
	v_add_f32_e32 v159, v159, v199
	s_waitcnt lgkmcnt(8)
	v_mfma_f32_32x32x16_bf16 v[64:79], v[248:251], v[120:123], v[64:79]
	ds_read_b128 v[248:251], v7 offset:24576
	v_mfma_f32_32x32x16_bf16 v[48:63], v[252:255], v[120:123], v[48:63]
	ds_read_b128 v[252:255], v7 offset:28672
	s_waitcnt lgkmcnt(8)
	v_mfma_f32_32x32x16_bf16 v[32:47], v[160:163], v[120:123], v[32:47]
	ds_read_b128 v[160:163], v8 offset:16384
	v_mfma_f32_32x32x16_bf16 v[16:31], v[164:167], v[120:123], v[16:31]
	ds_read_b128 v[164:167], v8 offset:20480
	s_cmp_lg_u32 s80, 0
	s_cbranch_scc1 .Lfa_fixO_b0
.Lfa_retO_b0:
	s_waitcnt lgkmcnt(8)
	v_mfma_f32_32x32x16_bf16 v[64:79], v[168:171], v[192:195], v[64:79]
	ds_read_b128 v[168:171], v8 offset:24576
	v_exp_f32_e32 v200, v200
	v_exp_f32_e32 v201, v201
	v_exp_f32_e32 v202, v202
	v_exp_f32_e32 v203, v203
	v_exp_f32_e32 v204, v204
	v_mfma_f32_32x32x16_bf16 v[48:63], v[224:227], v[192:195], v[48:63]
	ds_read_b128 v[224:227], v8 offset:28672
	v_exp_f32_e32 v205, v205
	v_exp_f32_e32 v206, v206
	v_exp_f32_e32 v207, v207
	v_add_f32_e32 v159, v159, v200
	v_add_f32_e32 v159, v159, v201
	s_waitcnt lgkmcnt(8)
	v_mfma_f32_32x32x16_bf16 v[32:47], v[228:231], v[192:195], v[32:47]
	ds_read_b128 v[228:231], v9 offset:16384
	v_add_f32_e32 v159, v159, v202
	v_add_f32_e32 v159, v159, v203
	v_cvt_pk_bf16_f32 v200, v200, v201
	v_cvt_pk_bf16_f32 v201, v202, v203
	v_add_f32_e32 v159, v159, v204
	v_mfma_f32_32x32x16_bf16 v[16:31], v[232:235], v[192:195], v[16:31]
	ds_read_b128 v[232:235], v9 offset:20480
	v_add_f32_e32 v159, v159, v205
	v_cvt_pk_bf16_f32 v202, v204, v205
	v_cvt_pk_bf16_f32 v203, v206, v207
	v_add_f32_e32 v159, v159, v206
	v_add_f32_e32 v159, v159, v207
	s_waitcnt lgkmcnt(8)
	v_mfma_f32_32x32x16_bf16 v[64:79], v[236:239], v[200:203], v[64:79]
	ds_read_b128 v[236:239], v9 offset:24576
	v_exp_f32_e32 v208, v208
	v_exp_f32_e32 v209, v209
	v_exp_f32_e32 v210, v210
	v_exp_f32_e32 v211, v211
	v_exp_f32_e32 v212, v212
	v_mfma_f32_32x32x16_bf16 v[48:63], v[244:247], v[200:203], v[48:63]
	ds_read_b128 v[244:247], v9 offset:28672
	v_exp_f32_e32 v213, v213
	v_exp_f32_e32 v214, v214
	v_exp_f32_e32 v215, v215
	v_add_f32_e32 v159, v159, v208
	v_add_f32_e32 v159, v159, v209
	s_waitcnt lgkmcnt(8)
	v_mfma_f32_32x32x16_bf16 v[32:47], v[248:251], v[200:203], v[32:47]
	v_add_f32_e32 v159, v159, v210
	v_add_f32_e32 v159, v159, v211
	v_cvt_pk_bf16_f32 v208, v208, v209
	v_cvt_pk_bf16_f32 v209, v210, v211
	v_add_f32_e32 v159, v159, v212
	v_mfma_f32_32x32x16_bf16 v[16:31], v[252:255], v[200:203], v[16:31]
	v_add_f32_e32 v159, v159, v213
	v_cvt_pk_bf16_f32 v210, v212, v213
	v_cvt_pk_bf16_f32 v211, v214, v215
	v_add_f32_e32 v159, v159, v214
	v_add_f32_e32 v159, v159, v215
	s_waitcnt lgkmcnt(6)
	v_mfma_f32_32x32x16_bf16 v[64:79], v[160:163], v[208:211], v[64:79]
	v_exp_f32_e32 v216, v216
	v_exp_f32_e32 v217, v217
	v_exp_f32_e32 v218, v218
	v_exp_f32_e32 v219, v219
	v_exp_f32_e32 v220, v220
	v_mfma_f32_32x32x16_bf16 v[48:63], v[164:167], v[208:211], v[48:63]
	v_exp_f32_e32 v221, v221
	v_exp_f32_e32 v222, v222
	v_exp_f32_e32 v223, v223
	v_add_f32_e32 v159, v159, v216
	v_add_f32_e32 v159, v159, v217
	s_waitcnt lgkmcnt(4)
	v_mfma_f32_32x32x16_bf16 v[32:47], v[168:171], v[208:211], v[32:47]
	v_add_f32_e32 v159, v159, v218
	v_add_f32_e32 v159, v159, v219
	v_cvt_pk_bf16_f32 v216, v216, v217
	v_cvt_pk_bf16_f32 v217, v218, v219
	v_add_f32_e32 v159, v159, v220
	v_mfma_f32_32x32x16_bf16 v[16:31], v[224:227], v[208:211], v[16:31]
	v_add_f32_e32 v159, v159, v221
	v_cvt_pk_bf16_f32 v218, v220, v221
	v_cvt_pk_bf16_f32 v219, v222, v223
	v_add_f32_e32 v159, v159, v222
	v_add_f32_e32 v159, v159, v223
	s_waitcnt lgkmcnt(2)
	v_mfma_f32_32x32x16_bf16 v[64:79], v[228:231], v[216:219], v[64:79]
	s_add_i32 s26, s26, 1
	s_add_u32 s6, s6, 0x8000
	v_mfma_f32_32x32x16_bf16 v[48:63], v[232:235], v[216:219], v[48:63]
	s_addc_u32 s7, s7, 0
	s_addk_i32 s8, 0x80
	s_waitcnt lgkmcnt(0)
	v_mfma_f32_32x32x16_bf16 v[32:47], v[236:239], v[216:219], v[32:47]
	v_add_u32_e32 v158, 0xffffff80, v158
	v_mfma_f32_32x32x16_bf16 v[16:31], v[244:247], v[216:219], v[16:31]
	s_cmp_eq_u32 s25, s26
	s_cbranch_scc0 .Lfa_top_b1
